# strategy 2: conversion loop store ladder de-serialised (8 LDS row reads issued together), windows unchanged
# speedup vs baseline: 1.0074x; 1.0019x over previous
; #define LAS __attribute__((address_space(3)))
; __device__ __forceinline__ void tr_item_cu(const float* __restrict__ W, int K, int N, bf16* __restrict__ WT, const float* rowgain, int mode, LAS unsigned char* buf, int item, int wave, int lane) {
;     ...
;     for (int m = 0; m < 8; ++m) { const int row = 16 * wave + 2 * m + hr;
;         const u32x4 o = *(const LAS u32x4*)(buf + row * TCP + c * 16);
;         asm volatile("global_store_dwordx4 %0, %1, off sc1\n\ts_nop 1" :: "v"(WT + (size_t)row_map(mode, n0 + row) * K + k0 + 8 * c), "v"(o) : "memory"); }
; __global__ void __launch_bounds__(NTHREADS, 2) mega_fwd(Args args) {
;     ...
;         for (int it = bid; it < DEPTH * I_LAYER; it += G, nbuf ^= 1) {
;             const int itr = DEPTH * I_LAYER - 1 - it;
;             const int l = itr / I_LAYER; int r = itr - l * I_LAYER;
;             unsigned char* WL = P_WL(l);
;             const float* W; int K, N, mode = 0; bf16* WT; const float* rg = nullptr;
;             if (r < 3 * I_GU) { const int w = r / I_GU; r -= w * I_GU;
;                 if (w < 2) { W = args.in[2 + w] + (size_t)l * D * FF; K = D; N = FF; WT = (bf16*)(WL + OFF_WGU1); rg = args.in[1] + (size_t)l * D; mode = 1 + w; }
;                 else { W = args.in[4] + (size_t)l * FF * D; K = FF; N = D; WT = (bf16*)(WL + OFF_WD1); } }
;             else if ((r -= 3 * I_GU) < 3 * I_GU) { const int w = r / I_GU; r -= w * I_GU;
;                 if (w < 2) { W = args.in[13 + w] + (size_t)l * D * FF; K = D; N = FF; WT = (bf16*)(WL + OFF_WGU2); rg = args.in[12] + (size_t)l * D; mode = 1 + w; }
;                 else { W = args.in[15] + (size_t)l * FF * D; K = FF; N = D; WT = (bf16*)(WL + OFF_WD2); } }
;             else if ((r -= 3 * I_GU) < I_IN) { W = args.in[6] + (size_t)l * D * INW; K = D; N = INW; WT = (bf16*)(WL + OFF_WIN); rg = args.in[5] + (size_t)l * D; mode = 3; }
;             else { r -= I_IN; W = args.in[11] + (size_t)l * D * D; K = D; N = D; WT = (bf16*)(WL + OFF_WOUT); }
;             tr_item_cu(W, K, N, WT, rg, mode, lds + nbuf * TC_BUF, r, wave, lane);
;         }
.LBB0_32:
	v_ashrrev_i32_e32 v8, 31, v9
	v_mul_lo_u32 v10, s21, v9
	v_mul_lo_u32 v11, s20, v8
	v_mad_u64_u32 v[8:9], s[20:21], s20, v9, 0
	s_load_dwordx4 s[20:23], s[0:1], 0x88
	v_add3_u32 v9, v9, v11, v10
	v_lshl_add_u64 v[6:7], v[8:9], 1, v[6:7]
	s_waitcnt lgkmcnt(0)
	global_store_dwordx4 v[6:7], v[48:51], off sc1
	s_nop 1
	s_xor_b32 s43, s43, 1
	s_add_i32 s44, s44, s100
	s_sub_i32 s38, s38, s100
	s_sub_i32 s39, s39, s100
	s_mov_b32 s100, s99
	s_cmp_gt_i32 s44, s101
	s_cbranch_scc1 .LBB0_184

; __device__ __forceinline__ unsigned cvt_pk_bf16(float lo, float hi) { unsigned r; asm volatile("v_cvt_pk_bf16_f32 %0, %1, %2" : "=v"(r) : "v"(lo), "v"(hi)); return r; }
; #define LAS __attribute__((address_space(3)))
; __device__ __forceinline__ void tr_item_cu(const float* __restrict__ W, int K, int N, bf16* __restrict__ WT, const float* rowgain, int mode, LAS unsigned char* buf, int item, int wave, int lane) {
;     ...
; #pragma unroll
;     for (int i = 0; i < 4; ++i) {
;         u32x4 lo, hi;
;         lo.x = pg8::cvt_pk_bf16(v[0][i], v[1][i]);   lo.y = pg8::cvt_pk_bf16(v[2][i], v[3][i]);   lo.z = pg8::cvt_pk_bf16(v[4][i], v[5][i]);   lo.w = pg8::cvt_pk_bf16(v[6][i], v[7][i]);
;         hi.x = pg8::cvt_pk_bf16(v[8][i], v[9][i]);   hi.y = pg8::cvt_pk_bf16(v[10][i], v[11][i]); hi.z = pg8::cvt_pk_bf16(v[12][i], v[13][i]); hi.w = pg8::cvt_pk_bf16(v[14][i], v[15][i]);
;         LAS unsigned char* p = buf + (4 * c + i) * TCP + kw * 2;
;         *(LAS u32x4*)p = lo; *(LAS u32x4*)(p + 16) = hi;
;     }
;     __syncthreads();
; #pragma unroll
;     for (int m = 0; m < 8; ++m) { const int row = 16 * wave + 2 * m + hr;
;         const u32x4 o = *(const LAS u32x4*)(buf + row * TCP + c * 16);
;         asm volatile("global_store_dwordx4 %0, %1, off sc1\n\ts_nop 1" :: "v"(WT + (size_t)row_map(mode, n0 + row) * K + k0 + 8 * c), "v"(o) : "memory"); }
.LBB0_57:
	s_mul_i32 s18, s43, 0x10800
	s_add_i32 s18, s18, 0
	s_waitcnt vmcnt(0)
	v_cvt_pk_bf16_f32 v120, v2, v6
	v_cvt_pk_bf16_f32 v121, v10, v14
	v_cvt_pk_bf16_f32 v122, v18, v22
	v_cvt_pk_bf16_f32 v123, v26, v30
	v_add3_u32 v10, s18, v75, v76
	v_cvt_pk_bf16_f32 v124, v34, v38
	v_cvt_pk_bf16_f32 v125, v42, v46
	v_cvt_pk_bf16_f32 v126, v58, v62
	v_cvt_pk_bf16_f32 v127, v50, v54
	ds_write_b128 v10, v[120:123]
	ds_write_b128 v10, v[124:127] offset:16
	v_cvt_pk_bf16_f32 v120, v3, v7
	v_cvt_pk_bf16_f32 v121, v11, v15
	v_cvt_pk_bf16_f32 v122, v19, v23
	v_cvt_pk_bf16_f32 v123, v27, v31
	v_cvt_pk_bf16_f32 v124, v35, v39
	v_cvt_pk_bf16_f32 v125, v43, v47
	v_cvt_pk_bf16_f32 v126, v59, v63
	v_cvt_pk_bf16_f32 v127, v51, v55
	ds_write_b128 v10, v[120:123] offset:528
	ds_write_b128 v10, v[124:127] offset:544
	v_cvt_pk_bf16_f32 v120, v4, v8
	v_cvt_pk_bf16_f32 v121, v12, v16
	v_cvt_pk_bf16_f32 v122, v20, v24
	v_cvt_pk_bf16_f32 v123, v28, v32
	v_cvt_pk_bf16_f32 v124, v36, v40
	v_cvt_pk_bf16_f32 v125, v44, v48
	v_cvt_pk_bf16_f32 v126, v60, v64
	v_cvt_pk_bf16_f32 v127, v52, v56
	ds_write_b128 v10, v[120:123] offset:1056
	ds_write_b128 v10, v[124:127] offset:1072
	v_cvt_pk_bf16_f32 v2, v5, v9
	v_cvt_pk_bf16_f32 v3, v13, v17
	v_cvt_pk_bf16_f32 v4, v21, v25
	v_cvt_pk_bf16_f32 v5, v29, v33
	v_cvt_pk_bf16_f32 v6, v37, v41
	v_cvt_pk_bf16_f32 v7, v45, v49
	v_cvt_pk_bf16_f32 v8, v61, v65
	v_cvt_pk_bf16_f32 v9, v53, v57
	ds_write_b128 v10, v[2:5] offset:1584
	ds_write_b128 v10, v[6:9] offset:1600
	v_add_u32_e32 v2, s18, v78
	v_add_u32_e32 v8, v2, v79
	s_waitcnt lgkmcnt(0)
	s_barrier
	ds_read_b128 v[20:23], v8
	ds_read_b128 v[24:27], v8 offset:1056
	ds_read_b128 v[28:31], v8 offset:2112
	ds_read_b128 v[32:35], v8 offset:3168
	ds_read_b128 v[36:39], v8 offset:4224
	ds_read_b128 v[40:43], v8 offset:5280
	ds_read_b128 v[44:47], v8 offset:6336
	ds_read_b128 v[48:51], v8 offset:7392
	s_cmp_lt_i32 s45, 1
	v_add_u32_e32 v6, s22, v77
	s_cbranch_scc1 .LBB0_62
	s_cmp_gt_i32 s45, 1
	s_cbranch_scc0 .LBB0_63
	s_cmp_eq_u32 s45, 2
	s_mov_b64 s[28:29], -1
	s_cbranch_scc0 .LBB0_61
	v_lshlrev_b32_e32 v7, 1, v6
	v_and_or_b32 v9, v7, s40, v109
	s_mov_b64 s[28:29], 0

; #define LAS __attribute__((address_space(3)))
; __device__ __forceinline__ void tr_item_cu(const float* __restrict__ W, int K, int N, bf16* __restrict__ WT, const float* rowgain, int mode, LAS unsigned char* buf, int item, int wave, int lane) {
;     ...
;     for (int m = 0; m < 8; ++m) { const int row = 16 * wave + 2 * m + hr;
;         const u32x4 o = *(const LAS u32x4*)(buf + row * TCP + c * 16);
;         asm volatile("global_store_dwordx4 %0, %1, off sc1\n\ts_nop 1" :: "v"(WT + (size_t)row_map(mode, n0 + row) * K + k0 + 8 * c), "v"(o) : "memory"); }
.LBB0_73:
	s_lshl_b64 s[26:27], s[26:27], 1
	s_add_u32 s24, s24, s26
	s_addc_u32 s25, s25, s27
	v_ashrrev_i32_e32 v10, 31, v9
	v_lshl_add_u64 v[6:7], s[24:25], 0, v[68:69]
	v_mul_lo_u32 v12, s21, v9
	v_mul_lo_u32 v13, s20, v10
	v_mad_u64_u32 v[10:11], s[24:25], s20, v9, 0
	v_add3_u32 v11, v11, v13, v12
	v_lshl_add_u64 v[10:11], v[10:11], 1, v[6:7]
	s_waitcnt lgkmcnt(0)
	global_store_dwordx4 v[10:11], v[20:23], off sc1
	s_nop 1
	s_cmp_lt_i32 s45, 1
	v_add_u32_e32 v9, s22, v82
	s_cbranch_scc1 .LBB0_78
	s_cmp_gt_i32 s45, 1
	s_cbranch_scc0 .LBB0_79
	s_cmp_eq_u32 s45, 2
	s_mov_b64 s[24:25], -1
	s_cbranch_scc0 .LBB0_77
	v_lshlrev_b32_e32 v10, 1, v9
	v_and_or_b32 v10, v10, s40, v110
	s_mov_b64 s[24:25], 0

; #define LAS __attribute__((address_space(3)))
; __device__ __forceinline__ void tr_item_cu(const float* __restrict__ W, int K, int N, bf16* __restrict__ WT, const float* rowgain, int mode, LAS unsigned char* buf, int item, int wave, int lane) {
;     ...
;     for (int m = 0; m < 8; ++m) { const int row = 16 * wave + 2 * m + hr;
;         const u32x4 o = *(const LAS u32x4*)(buf + row * TCP + c * 16);
;         asm volatile("global_store_dwordx4 %0, %1, off sc1\n\ts_nop 1" :: "v"(WT + (size_t)row_map(mode, n0 + row) * K + k0 + 8 * c), "v"(o) : "memory"); }
.LBB0_89:
	v_ashrrev_i32_e32 v9, 31, v10
	v_mul_lo_u32 v12, s21, v10
	v_mul_lo_u32 v9, s20, v9
	v_mad_u64_u32 v[10:11], s[24:25], s20, v10, 0
	v_add3_u32 v11, v11, v9, v12
	v_lshl_add_u64 v[10:11], v[10:11], 1, v[6:7]
	s_waitcnt lgkmcnt(0)
	global_store_dwordx4 v[10:11], v[24:27], off sc1
	s_nop 1
	s_cmp_lt_i32 s45, 1
	v_add_u32_e32 v9, s22, v86
	s_cbranch_scc1 .LBB0_94
	s_cmp_gt_i32 s45, 1
	s_cbranch_scc0 .LBB0_95
	s_cmp_eq_u32 s45, 2
	s_mov_b64 s[24:25], -1
	s_cbranch_scc0 .LBB0_93
	v_lshlrev_b32_e32 v10, 1, v9
	v_and_or_b32 v10, v10, s40, v111
	s_mov_b64 s[24:25], 0

; #define LAS __attribute__((address_space(3)))
; __device__ __forceinline__ void tr_item_cu(const float* __restrict__ W, int K, int N, bf16* __restrict__ WT, const float* rowgain, int mode, LAS unsigned char* buf, int item, int wave, int lane) {
;     ...
;     for (int m = 0; m < 8; ++m) { const int row = 16 * wave + 2 * m + hr;
;         const u32x4 o = *(const LAS u32x4*)(buf + row * TCP + c * 16);
;         asm volatile("global_store_dwordx4 %0, %1, off sc1\n\ts_nop 1" :: "v"(WT + (size_t)row_map(mode, n0 + row) * K + k0 + 8 * c), "v"(o) : "memory"); }
.LBB0_105:
	v_ashrrev_i32_e32 v9, 31, v10
	v_mul_lo_u32 v12, s21, v10
	v_mul_lo_u32 v9, s20, v9
	v_mad_u64_u32 v[10:11], s[24:25], s20, v10, 0
	v_add3_u32 v11, v11, v9, v12
	v_lshl_add_u64 v[10:11], v[10:11], 1, v[6:7]
	s_waitcnt lgkmcnt(0)
	global_store_dwordx4 v[10:11], v[28:31], off sc1
	s_nop 1
	s_cmp_lt_i32 s45, 1
	v_add_u32_e32 v9, s22, v90
	s_cbranch_scc1 .LBB0_110
	s_cmp_gt_i32 s45, 1
	s_cbranch_scc0 .LBB0_111
	s_cmp_eq_u32 s45, 2
	s_mov_b64 s[24:25], -1
	s_cbranch_scc0 .LBB0_109
	v_lshlrev_b32_e32 v10, 1, v9
	v_and_or_b32 v10, v10, s40, v112
	s_mov_b64 s[24:25], 0

; #define LAS __attribute__((address_space(3)))
; __device__ __forceinline__ void tr_item_cu(const float* __restrict__ W, int K, int N, bf16* __restrict__ WT, const float* rowgain, int mode, LAS unsigned char* buf, int item, int wave, int lane) {
;     ...
;     for (int m = 0; m < 8; ++m) { const int row = 16 * wave + 2 * m + hr;
;         const u32x4 o = *(const LAS u32x4*)(buf + row * TCP + c * 16);
;         asm volatile("global_store_dwordx4 %0, %1, off sc1\n\ts_nop 1" :: "v"(WT + (size_t)row_map(mode, n0 + row) * K + k0 + 8 * c), "v"(o) : "memory"); }
.LBB0_121:
	v_ashrrev_i32_e32 v9, 31, v10
	v_mul_lo_u32 v12, s21, v10
	v_mul_lo_u32 v9, s20, v9
	v_mad_u64_u32 v[10:11], s[24:25], s20, v10, 0
	v_add3_u32 v11, v11, v9, v12
	v_lshl_add_u64 v[10:11], v[10:11], 1, v[6:7]
	s_waitcnt lgkmcnt(0)
	global_store_dwordx4 v[10:11], v[32:35], off sc1
	s_nop 1
	s_cmp_lt_i32 s45, 1
	v_add_u32_e32 v9, s22, v94
	s_cbranch_scc1 .LBB0_126
	s_cmp_gt_i32 s45, 1
	s_cbranch_scc0 .LBB0_127
	s_cmp_eq_u32 s45, 2
	s_mov_b64 s[24:25], -1
	s_cbranch_scc0 .LBB0_125
	v_lshlrev_b32_e32 v10, 1, v9
	v_and_or_b32 v10, v10, s40, v113
	s_mov_b64 s[24:25], 0

; #define LAS __attribute__((address_space(3)))
; __device__ __forceinline__ void tr_item_cu(const float* __restrict__ W, int K, int N, bf16* __restrict__ WT, const float* rowgain, int mode, LAS unsigned char* buf, int item, int wave, int lane) {
;     ...
;     for (int m = 0; m < 8; ++m) { const int row = 16 * wave + 2 * m + hr;
;         const u32x4 o = *(const LAS u32x4*)(buf + row * TCP + c * 16);
;         asm volatile("global_store_dwordx4 %0, %1, off sc1\n\ts_nop 1" :: "v"(WT + (size_t)row_map(mode, n0 + row) * K + k0 + 8 * c), "v"(o) : "memory"); }
.LBB0_137:
	v_ashrrev_i32_e32 v9, 31, v10
	v_mul_lo_u32 v12, s21, v10
	v_mul_lo_u32 v9, s20, v9
	v_mad_u64_u32 v[10:11], s[24:25], s20, v10, 0
	v_add3_u32 v11, v11, v9, v12
	v_lshl_add_u64 v[10:11], v[10:11], 1, v[6:7]
	s_waitcnt lgkmcnt(0)
	global_store_dwordx4 v[10:11], v[36:39], off sc1
	s_nop 1
	s_cmp_lt_i32 s45, 1
	v_add_u32_e32 v9, s22, v97
	s_cbranch_scc1 .LBB0_142
	s_cmp_gt_i32 s45, 1
	s_cbranch_scc0 .LBB0_143
	s_cmp_eq_u32 s45, 2
	s_mov_b64 s[24:25], -1
	s_cbranch_scc0 .LBB0_141
	v_lshlrev_b32_e32 v10, 1, v9
	v_and_or_b32 v10, v10, s40, v114
	s_mov_b64 s[24:25], 0

; #define LAS __attribute__((address_space(3)))
; __device__ __forceinline__ void tr_item_cu(const float* __restrict__ W, int K, int N, bf16* __restrict__ WT, const float* rowgain, int mode, LAS unsigned char* buf, int item, int wave, int lane) {
;     ...
;     for (int m = 0; m < 8; ++m) { const int row = 16 * wave + 2 * m + hr;
;         const u32x4 o = *(const LAS u32x4*)(buf + row * TCP + c * 16);
;         asm volatile("global_store_dwordx4 %0, %1, off sc1\n\ts_nop 1" :: "v"(WT + (size_t)row_map(mode, n0 + row) * K + k0 + 8 * c), "v"(o) : "memory"); }
.LBB0_153:
	v_ashrrev_i32_e32 v9, 31, v10
	v_mul_lo_u32 v12, s21, v10
	v_mul_lo_u32 v9, s20, v9
	v_mad_u64_u32 v[10:11], s[24:25], s20, v10, 0
	v_add3_u32 v11, v11, v9, v12
	v_lshl_add_u64 v[10:11], v[10:11], 1, v[6:7]
	s_waitcnt lgkmcnt(0)
	global_store_dwordx4 v[10:11], v[40:43], off sc1
	s_nop 1
	s_cmp_lt_i32 s45, 1
	v_add_u32_e32 v9, s22, v101
	s_cbranch_scc1 .LBB0_158
	s_cmp_gt_i32 s45, 1
	s_cbranch_scc0 .LBB0_159
	s_cmp_eq_u32 s45, 2
	s_mov_b64 s[24:25], -1
	s_cbranch_scc0 .LBB0_157
	v_lshlrev_b32_e32 v10, 1, v9
	v_and_or_b32 v10, v10, s40, v115
	s_mov_b64 s[24:25], 0

; #define LAS __attribute__((address_space(3)))
; __device__ __forceinline__ void tr_item_cu(const float* __restrict__ W, int K, int N, bf16* __restrict__ WT, const float* rowgain, int mode, LAS unsigned char* buf, int item, int wave, int lane) {
;     ...
;     for (int m = 0; m < 8; ++m) { const int row = 16 * wave + 2 * m + hr;
;         const u32x4 o = *(const LAS u32x4*)(buf + row * TCP + c * 16);
;         asm volatile("global_store_dwordx4 %0, %1, off sc1\n\ts_nop 1" :: "v"(WT + (size_t)row_map(mode, n0 + row) * K + k0 + 8 * c), "v"(o) : "memory"); }
.LBB0_169:
	v_ashrrev_i32_e32 v9, 31, v10
	v_mul_lo_u32 v12, s21, v10
	v_mul_lo_u32 v9, s20, v9
	v_mad_u64_u32 v[10:11], s[24:25], s20, v10, 0
	v_add3_u32 v11, v11, v9, v12
	v_lshl_add_u64 v[10:11], v[10:11], 1, v[6:7]
	s_waitcnt lgkmcnt(0)
	global_store_dwordx4 v[10:11], v[44:47], off sc1
	s_nop 1
	s_cmp_lt_i32 s45, 1
	v_add_u32_e32 v8, s22, v105
	s_cbranch_scc1 .LBB0_174
	s_cmp_gt_i32 s45, 1
	s_cbranch_scc0 .LBB0_175
	s_cmp_eq_u32 s45, 2
	s_mov_b64 s[22:23], -1
	s_cbranch_scc0 .LBB0_173
	v_lshlrev_b32_e32 v9, 1, v8
	v_and_or_b32 v9, v9, s40, v116
	s_mov_b64 s[22:23], 0
